# FFN1 epilogue stores widened only (dwordx2 pairs -> dwordx4 via v_permlane16_swap)
# speedup vs baseline: 1.0087x; 1.0087x over previous
; __device__ __forceinline__ float rstd16(const float* part, int row) {
;     const f32x4* p = (const f32x4*)(part + (size_t)row * 16); const f32x4 a = p[0], b = p[1], c = p[2], d = p[3];
;     const float s = ((a.x + a.y) + (a.z + a.w)) + ((b.x + b.y) + (b.z + b.w)) + ((c.x + c.y) + (c.z + c.w)) + ((d.x + d.y) + (d.z + d.w));
;     return rsqrtf(s * (1.f / 1024.f) + 1e-6f);
; }
.LBB0_2477:
	v_mbcnt_lo_u32_b32 v231, -1, 0
	v_mbcnt_hi_u32_b32 v231, -1, v231
	v_bfe_u32 v231, v231, 4, 1
	v_mul_u32_u24_e32 v230, 0x15ff8, v231
	v_mov_b32_e32 v231, 0
	v_lshl_or_b32 v138, s49, 8, v155
	v_ashrrev_i32_e32 v142, 1, v138
	v_lshl_add_u32 v138, s48, 8, v141
	v_ashrrev_i32_e32 v143, 31, v142
	v_ashrrev_i32_e32 v139, 31, v138
	v_readlane_b32 s28, v254, 8
	v_lshlrev_b64 v[158:159], 6, v[138:139]
	v_readlane_b32 s29, v254, 9
	s_mov_b32 s48, 0x800000
	s_movk_i32 s49, 0x1600
	v_lshl_add_u64 v[166:167], s[28:29], 0, v[158:159]
	v_mbcnt_lo_u32_b32 v164, -1, 0
	v_mbcnt_hi_u32_b32 v164, -1, v164
	v_and_b32_e32 v165, 48, v164
	v_xor_b32_e32 v216, 16, v164
	v_xor_b32_e32 v217, 32, v164
	v_lshlrev_b32_e32 v216, 2, v216
	v_lshlrev_b32_e32 v217, 2, v217
	v_mov_b32_e32 v164, v138
	v_lshl_or_b32 v164, v164, 6, v165
	global_load_dwordx4 v[160:163], v164, s[28:29]
	v_add_u32_e32 v164, 16, v138
	v_lshl_or_b32 v164, v164, 6, v165
	global_load_dwordx4 v[188:191], v164, s[28:29]
	v_add_u32_e32 v164, 32, v138
	v_lshl_or_b32 v164, v164, 6, v165
	global_load_dwordx4 v[192:195], v164, s[28:29]
	v_add_u32_e32 v164, 48, v138
	v_lshl_or_b32 v164, v164, 6, v165
	global_load_dwordx4 v[196:199], v164, s[28:29]
	v_add_u32_e32 v164, 128, v138
	v_lshl_or_b32 v164, v164, 6, v165
	global_load_dwordx4 v[200:203], v164, s[28:29]
	v_add_u32_e32 v164, 144, v138
	v_lshl_or_b32 v164, v164, 6, v165
	global_load_dwordx4 v[204:207], v164, s[28:29]
	v_add_u32_e32 v164, 160, v138
	v_lshl_or_b32 v164, v164, 6, v165
	global_load_dwordx4 v[208:211], v164, s[28:29]
	v_add_u32_e32 v164, 176, v138
	v_lshl_or_b32 v164, v164, 6, v165
	global_load_dwordx4 v[212:215], v164, s[28:29]
	s_waitcnt vmcnt(0)
	v_pk_add_f32 v[160:161], v[160:161], v[162:163]
	v_pk_add_f32 v[188:189], v[188:189], v[190:191]
	v_pk_add_f32 v[192:193], v[192:193], v[194:195]
	v_pk_add_f32 v[196:197], v[196:197], v[198:199]
	v_pk_add_f32 v[200:201], v[200:201], v[202:203]
	v_pk_add_f32 v[204:205], v[204:205], v[206:207]
	v_pk_add_f32 v[208:209], v[208:209], v[210:211]
	v_pk_add_f32 v[212:213], v[212:213], v[214:215]
	v_add_f32_e32 v160, v160, v161
	v_add_f32_e32 v188, v188, v189
	v_add_f32_e32 v192, v192, v193
	v_add_f32_e32 v196, v196, v197
	v_add_f32_e32 v200, v200, v201
	v_add_f32_e32 v204, v204, v205
	v_add_f32_e32 v208, v208, v209
	v_add_f32_e32 v212, v212, v213
	ds_bpermute_b32 v161, v216, v160
	ds_bpermute_b32 v189, v216, v188
	ds_bpermute_b32 v193, v216, v192
	ds_bpermute_b32 v197, v216, v196
	ds_bpermute_b32 v201, v216, v200
	ds_bpermute_b32 v205, v216, v204
	ds_bpermute_b32 v209, v216, v208
	ds_bpermute_b32 v213, v216, v212
	s_waitcnt lgkmcnt(0)
	v_add_f32_e32 v160, v160, v161
	v_add_f32_e32 v188, v188, v189
	v_add_f32_e32 v192, v192, v193
	v_add_f32_e32 v196, v196, v197
	v_add_f32_e32 v200, v200, v201
	v_add_f32_e32 v204, v204, v205
	v_add_f32_e32 v208, v208, v209
	v_add_f32_e32 v212, v212, v213
	ds_bpermute_b32 v161, v217, v160
	ds_bpermute_b32 v189, v217, v188
	ds_bpermute_b32 v193, v217, v192
	ds_bpermute_b32 v197, v217, v196
	ds_bpermute_b32 v201, v217, v200
	ds_bpermute_b32 v205, v217, v204
	ds_bpermute_b32 v209, v217, v208
	ds_bpermute_b32 v213, v217, v212
	s_waitcnt lgkmcnt(0)
	v_add_f32_e32 v160, v160, v161
	v_add_f32_e32 v188, v188, v189
	v_add_f32_e32 v192, v192, v193
	v_add_f32_e32 v196, v196, v197
	v_add_f32_e32 v200, v200, v201
	v_add_f32_e32 v204, v204, v205
	v_add_f32_e32 v208, v208, v209
	v_add_f32_e32 v212, v212, v213
	v_fmamk_f32 v160, v160, 0x3a800000, v171
	v_fmamk_f32 v188, v188, 0x3a800000, v171
	v_fmamk_f32 v192, v192, 0x3a800000, v171
	v_fmamk_f32 v196, v196, 0x3a800000, v171
	v_fmamk_f32 v200, v200, 0x3a800000, v171
	v_fmamk_f32 v204, v204, 0x3a800000, v171
	v_fmamk_f32 v208, v208, 0x3a800000, v171
	v_fmamk_f32 v212, v212, 0x3a800000, v171
	v_rsq_f32_e32 v163, v160
	v_rsq_f32_e32 v191, v188
	v_rsq_f32_e32 v195, v192
	v_rsq_f32_e32 v199, v196
	v_rsq_f32_e32 v203, v200
	v_rsq_f32_e32 v207, v204
	v_rsq_f32_e32 v211, v208
	v_rsq_f32_e32 v215, v212
	s_nop 0
	s_nop 0
	s_nop 0
	s_nop 0
	v_mov_b32_e32 v140, v163
	v_pk_mul_f32 v[124:125], v[124:125], v[140:141] op_sel_hi:[1,0]
	v_pk_mul_f32 v[120:121], v[120:121], v[140:141] op_sel_hi:[1,0]
	v_mul_f32_e32 v139, 0xbfb8aa3b, v124
	v_exp_f32_e32 v139, v139
	v_pk_mul_f32 v[122:123], v[122:123], v[140:141] op_sel_hi:[1,0]
	v_pk_mul_f32 v[116:117], v[116:117], v[140:141] op_sel_hi:[1,0]
	v_pk_mul_f32 v[112:113], v[112:113], v[140:141] op_sel_hi:[1,0]
	v_add_f32_e32 v139, 1.0, v139
	v_rcp_f32_e32 v158, v139
	v_mul_f32_e32 v139, 0xbfb8aa3b, v125
	v_exp_f32_e32 v139, v139
	v_pk_mul_f32 v[114:115], v[114:115], v[140:141] op_sel_hi:[1,0]
	v_add_f32_e32 v139, 1.0, v139
	v_rcp_f32_e32 v159, v139
	s_nop 0
	v_pk_mul_f32 v[124:125], v[124:125], v[158:159]
	s_nop 0
	v_pk_mul_f32 v[120:121], v[120:121], v[124:125]
	v_pk_mul_f32 v[124:125], v[126:127], v[140:141] op_sel_hi:[1,0]
	s_nop 0
	v_mul_f32_e32 v126, 0xbfb8aa3b, v124
	v_mul_f32_e32 v127, 0xbfb8aa3b, v125
	v_exp_f32_e32 v126, v126
	v_exp_f32_e32 v127, v127
	v_add_f32_e32 v126, 1.0, v126
	v_add_f32_e32 v127, 1.0, v127
	v_rcp_f32_e32 v126, v126
	v_rcp_f32_e32 v127, v127
	s_nop 0
	v_pk_mul_f32 v[124:125], v[124:125], v[126:127]
	s_nop 0
	v_pk_mul_f32 v[122:123], v[122:123], v[124:125]
	v_cvt_pk_bf16_f32 v124, v120, v121
	v_mov_b64_e32 v[120:121], s[16:17]
	v_cvt_pk_bf16_f32 v125, v122, v123
	v_mad_i64_i32 v[126:127], s[26:27], v138, s49, v[120:121]
	v_lshlrev_b64 v[122:123], 1, v[142:143]
	v_lshl_add_u64 v[126:127], v[126:127], 0, v[122:123]
	v_lshl_add_u64 v[228:229], v[126:127], 0, v[230:231]
	v_mov_b64_e32 v[220:221], v[124:125]
	v_mul_f32_e32 v124, 0xbfb8aa3b, v116
	v_mul_f32_e32 v125, 0xbfb8aa3b, v117
	v_exp_f32_e32 v124, v124
	v_exp_f32_e32 v125, v125
	v_add_f32_e32 v124, 1.0, v124
	v_add_f32_e32 v125, 1.0, v125
	v_rcp_f32_e32 v124, v124
	v_rcp_f32_e32 v125, v125
	s_nop 0
	v_pk_mul_f32 v[116:117], v[116:117], v[124:125]
	s_nop 0
	v_pk_mul_f32 v[112:113], v[112:113], v[116:117]
	v_pk_mul_f32 v[116:117], v[118:119], v[140:141] op_sel_hi:[1,0]
	v_cvt_pk_bf16_f32 v112, v112, v113
	v_mul_f32_e32 v118, 0xbfb8aa3b, v116
	v_mul_f32_e32 v119, 0xbfb8aa3b, v117
	v_exp_f32_e32 v118, v118
	v_exp_f32_e32 v119, v119
	v_add_f32_e32 v118, 1.0, v118
	v_add_f32_e32 v119, 1.0, v119
	v_rcp_f32_e32 v118, v118
	v_rcp_f32_e32 v119, v119
	s_nop 0
	v_pk_mul_f32 v[116:117], v[116:117], v[118:119]
	s_nop 0
	v_pk_mul_f32 v[114:115], v[114:115], v[116:117]
	s_nop 0
	v_cvt_pk_bf16_f32 v113, v114, v115
	v_mov_b64_e32 v[224:225], v[112:113]
	v_or_b32_e32 v114, 16, v138
	v_ashrrev_i32_e32 v115, 31, v114
	v_lshlrev_b64 v[112:113], 6, v[114:115]
	v_lshl_add_u64 v[112:113], s[28:29], 0, v[112:113]
	s_nop 0
	s_nop 0
	s_nop 0
	s_nop 0
	v_mov_b32_e32 v112, v191
	v_pk_mul_f32 v[108:109], v[108:109], v[112:113] op_sel_hi:[1,0]
	s_nop 0
	v_mul_f32_e32 v113, 0xbfb8aa3b, v108
	v_exp_f32_e32 v113, v113
	s_nop 0
	v_add_f32_e32 v113, 1.0, v113
	v_rcp_f32_e32 v116, v113
	v_mul_f32_e32 v113, 0xbfb8aa3b, v109
	v_exp_f32_e32 v113, v113
	s_nop 0
	v_add_f32_e32 v113, 1.0, v113
	v_rcp_f32_e32 v117, v113
	v_pk_mul_f32 v[104:105], v[104:105], v[112:113] op_sel_hi:[1,0]
	v_pk_mul_f32 v[106:107], v[106:107], v[112:113] op_sel_hi:[1,0]
	v_pk_mul_f32 v[100:101], v[100:101], v[112:113] op_sel_hi:[1,0]
	v_pk_mul_f32 v[108:109], v[108:109], v[116:117]
	v_pk_mul_f32 v[96:97], v[96:97], v[112:113] op_sel_hi:[1,0]
	v_pk_mul_f32 v[104:105], v[104:105], v[108:109]
	v_pk_mul_f32 v[108:109], v[110:111], v[112:113] op_sel_hi:[1,0]
	v_pk_mul_f32 v[98:99], v[98:99], v[112:113] op_sel_hi:[1,0]
	v_mul_f32_e32 v110, 0xbfb8aa3b, v108
	v_mul_f32_e32 v111, 0xbfb8aa3b, v109
	v_exp_f32_e32 v110, v110
	v_exp_f32_e32 v111, v111
	v_add_f32_e32 v110, 1.0, v110
	v_add_f32_e32 v111, 1.0, v111
	v_rcp_f32_e32 v110, v110
	v_rcp_f32_e32 v111, v111
	s_nop 0
	v_pk_mul_f32 v[108:109], v[108:109], v[110:111]
	s_nop 0
	v_pk_mul_f32 v[106:107], v[106:107], v[108:109]
	v_cvt_pk_bf16_f32 v108, v104, v105
	v_cvt_pk_bf16_f32 v109, v106, v107
	v_mul_f32_e32 v106, 0xbfb8aa3b, v100
	v_mul_f32_e32 v107, 0xbfb8aa3b, v101
	v_exp_f32_e32 v106, v106
	v_exp_f32_e32 v107, v107
	v_mad_i64_i32 v[104:105], s[26:27], v114, s49, v[120:121]
	v_add_f32_e32 v106, 1.0, v106
	v_add_f32_e32 v107, 1.0, v107
	v_rcp_f32_e32 v106, v106
	v_rcp_f32_e32 v107, v107
	v_lshl_add_u64 v[104:105], v[104:105], 0, v[122:123]
	v_mov_b64_e32 v[222:223], v[108:109]
	s_nop 1
	v_permlane16_swap_b32_e32 v220, v222
	v_permlane16_swap_b32_e32 v221, v223
	global_store_dwordx4 v[228:229], v[220:223], off
	v_pk_mul_f32 v[100:101], v[100:101], v[106:107]
	s_nop 0
	v_pk_mul_f32 v[96:97], v[96:97], v[100:101]
	v_pk_mul_f32 v[100:101], v[102:103], v[112:113] op_sel_hi:[1,0]
	v_cvt_pk_bf16_f32 v96, v96, v97
	v_mul_f32_e32 v102, 0xbfb8aa3b, v100
	v_mul_f32_e32 v103, 0xbfb8aa3b, v101
	v_exp_f32_e32 v102, v102
	v_exp_f32_e32 v103, v103
	v_add_f32_e32 v102, 1.0, v102
	v_add_f32_e32 v103, 1.0, v103
	v_rcp_f32_e32 v102, v102
	v_rcp_f32_e32 v103, v103
	s_nop 0
	v_pk_mul_f32 v[100:101], v[100:101], v[102:103]
	s_nop 0
	v_pk_mul_f32 v[98:99], v[98:99], v[100:101]
	s_nop 0
	v_cvt_pk_bf16_f32 v97, v98, v99
	v_mov_b64_e32 v[226:227], v[96:97]
	s_nop 1
	v_permlane16_swap_b32_e32 v224, v226
	v_permlane16_swap_b32_e32 v225, v227
	global_store_dwordx4 v[228:229], v[224:227], off offset:128
	v_or_b32_e32 v98, 32, v138
	v_ashrrev_i32_e32 v99, 31, v98
	v_lshlrev_b64 v[96:97], 6, v[98:99]
	v_lshl_add_u64 v[96:97], s[28:29], 0, v[96:97]
	s_nop 0
	s_nop 0
	s_nop 0
	s_nop 0
	v_mov_b32_e32 v96, v195
	v_pk_mul_f32 v[92:93], v[92:93], v[96:97] op_sel_hi:[1,0]
	s_nop 0
	v_mul_f32_e32 v97, 0xbfb8aa3b, v92
	v_exp_f32_e32 v97, v97
	s_nop 0
	v_add_f32_e32 v97, 1.0, v97
	v_rcp_f32_e32 v100, v97
	v_mul_f32_e32 v97, 0xbfb8aa3b, v93
	v_exp_f32_e32 v97, v97
	s_nop 0
	v_add_f32_e32 v97, 1.0, v97
	v_rcp_f32_e32 v101, v97
	v_pk_mul_f32 v[88:89], v[88:89], v[96:97] op_sel_hi:[1,0]
	v_pk_mul_f32 v[90:91], v[90:91], v[96:97] op_sel_hi:[1,0]
	v_pk_mul_f32 v[84:85], v[84:85], v[96:97] op_sel_hi:[1,0]
	v_pk_mul_f32 v[92:93], v[92:93], v[100:101]
	v_pk_mul_f32 v[80:81], v[80:81], v[96:97] op_sel_hi:[1,0]
	v_pk_mul_f32 v[88:89], v[88:89], v[92:93]
	v_pk_mul_f32 v[92:93], v[94:95], v[96:97] op_sel_hi:[1,0]
	v_pk_mul_f32 v[82:83], v[82:83], v[96:97] op_sel_hi:[1,0]
	v_mul_f32_e32 v94, 0xbfb8aa3b, v92
	v_mul_f32_e32 v95, 0xbfb8aa3b, v93
	v_exp_f32_e32 v94, v94
	v_exp_f32_e32 v95, v95
	v_add_f32_e32 v94, 1.0, v94
	v_add_f32_e32 v95, 1.0, v95
	v_rcp_f32_e32 v94, v94
	v_rcp_f32_e32 v95, v95
	s_nop 0
	v_pk_mul_f32 v[92:93], v[92:93], v[94:95]
	s_nop 0
	v_pk_mul_f32 v[90:91], v[90:91], v[92:93]
	v_cvt_pk_bf16_f32 v92, v88, v89
	v_cvt_pk_bf16_f32 v93, v90, v91
	v_mul_f32_e32 v90, 0xbfb8aa3b, v84
	v_mul_f32_e32 v91, 0xbfb8aa3b, v85
	v_exp_f32_e32 v90, v90
	v_exp_f32_e32 v91, v91
	v_mad_i64_i32 v[88:89], s[26:27], v98, s49, v[120:121]
	v_add_f32_e32 v90, 1.0, v90
	v_add_f32_e32 v91, 1.0, v91
	v_rcp_f32_e32 v90, v90
	v_rcp_f32_e32 v91, v91
	v_lshl_add_u64 v[88:89], v[88:89], 0, v[122:123]
	v_lshl_add_u64 v[228:229], v[88:89], 0, v[230:231]
	v_mov_b64_e32 v[220:221], v[92:93]
	v_pk_mul_f32 v[84:85], v[84:85], v[90:91]
	s_nop 0
	v_pk_mul_f32 v[80:81], v[80:81], v[84:85]
	v_pk_mul_f32 v[84:85], v[86:87], v[96:97] op_sel_hi:[1,0]
	v_cvt_pk_bf16_f32 v80, v80, v81
	v_mul_f32_e32 v86, 0xbfb8aa3b, v84
	v_mul_f32_e32 v87, 0xbfb8aa3b, v85
	v_exp_f32_e32 v86, v86
	v_exp_f32_e32 v87, v87
	v_add_f32_e32 v86, 1.0, v86
	v_add_f32_e32 v87, 1.0, v87
	v_rcp_f32_e32 v86, v86
	v_rcp_f32_e32 v87, v87
	s_nop 0
	v_pk_mul_f32 v[84:85], v[84:85], v[86:87]
	s_nop 0
	v_pk_mul_f32 v[82:83], v[82:83], v[84:85]
	s_nop 0
	v_cvt_pk_bf16_f32 v81, v82, v83
	v_mov_b64_e32 v[224:225], v[80:81]
	v_or_b32_e32 v82, 48, v138
	v_ashrrev_i32_e32 v83, 31, v82
	v_lshlrev_b64 v[80:81], 6, v[82:83]
	v_lshl_add_u64 v[80:81], s[28:29], 0, v[80:81]
	s_nop 0
	s_nop 0
	s_nop 0
	s_nop 0
	v_mov_b32_e32 v80, v199
	v_pk_mul_f32 v[76:77], v[76:77], v[80:81] op_sel_hi:[1,0]
	s_nop 0
	v_mul_f32_e32 v81, 0xbfb8aa3b, v76
	v_exp_f32_e32 v81, v81
	s_nop 0
	v_add_f32_e32 v81, 1.0, v81
	v_rcp_f32_e32 v84, v81
	v_mul_f32_e32 v81, 0xbfb8aa3b, v77
	v_exp_f32_e32 v81, v81
	s_nop 0
	v_add_f32_e32 v81, 1.0, v81
	v_rcp_f32_e32 v85, v81
	v_pk_mul_f32 v[72:73], v[72:73], v[80:81] op_sel_hi:[1,0]
	v_pk_mul_f32 v[74:75], v[74:75], v[80:81] op_sel_hi:[1,0]
	v_pk_mul_f32 v[68:69], v[68:69], v[80:81] op_sel_hi:[1,0]
	v_pk_mul_f32 v[76:77], v[76:77], v[84:85]
	v_pk_mul_f32 v[64:65], v[64:65], v[80:81] op_sel_hi:[1,0]
	v_pk_mul_f32 v[72:73], v[72:73], v[76:77]
	v_pk_mul_f32 v[76:77], v[78:79], v[80:81] op_sel_hi:[1,0]
	v_pk_mul_f32 v[66:67], v[66:67], v[80:81] op_sel_hi:[1,0]
	v_mul_f32_e32 v78, 0xbfb8aa3b, v76
	v_mul_f32_e32 v79, 0xbfb8aa3b, v77
	v_exp_f32_e32 v78, v78
	v_exp_f32_e32 v79, v79
	v_add_f32_e32 v78, 1.0, v78
	v_add_f32_e32 v79, 1.0, v79
	v_rcp_f32_e32 v78, v78
	v_rcp_f32_e32 v79, v79
	s_nop 0
	v_pk_mul_f32 v[76:77], v[76:77], v[78:79]
	s_nop 0
	v_pk_mul_f32 v[74:75], v[74:75], v[76:77]
	v_cvt_pk_bf16_f32 v76, v72, v73
	v_cvt_pk_bf16_f32 v77, v74, v75
	v_mul_f32_e32 v74, 0xbfb8aa3b, v68
	v_mul_f32_e32 v75, 0xbfb8aa3b, v69
	v_exp_f32_e32 v74, v74
	v_exp_f32_e32 v75, v75
	v_mad_i64_i32 v[72:73], s[26:27], v82, s49, v[120:121]
	v_add_f32_e32 v74, 1.0, v74
	v_add_f32_e32 v75, 1.0, v75
	v_rcp_f32_e32 v74, v74
	v_rcp_f32_e32 v75, v75
	v_lshl_add_u64 v[72:73], v[72:73], 0, v[122:123]
	v_mov_b64_e32 v[222:223], v[76:77]
	s_nop 1
	v_permlane16_swap_b32_e32 v220, v222
	v_permlane16_swap_b32_e32 v221, v223
	global_store_dwordx4 v[228:229], v[220:223], off
	v_pk_mul_f32 v[68:69], v[68:69], v[74:75]
	s_nop 0
	v_pk_mul_f32 v[64:65], v[64:65], v[68:69]
	v_pk_mul_f32 v[68:69], v[70:71], v[80:81] op_sel_hi:[1,0]
	v_cvt_pk_bf16_f32 v64, v64, v65
	v_mul_f32_e32 v70, 0xbfb8aa3b, v68
	v_mul_f32_e32 v71, 0xbfb8aa3b, v69
	v_exp_f32_e32 v70, v70
	v_exp_f32_e32 v71, v71
	v_add_f32_e32 v70, 1.0, v70
	v_add_f32_e32 v71, 1.0, v71
	v_rcp_f32_e32 v70, v70
	v_rcp_f32_e32 v71, v71
	s_nop 0
	v_pk_mul_f32 v[68:69], v[68:69], v[70:71]
	s_nop 0
	v_pk_mul_f32 v[66:67], v[66:67], v[68:69]
	s_nop 0
	v_cvt_pk_bf16_f32 v65, v66, v67
	v_mov_b64_e32 v[226:227], v[64:65]
	s_nop 1
	v_permlane16_swap_b32_e32 v224, v226
	v_permlane16_swap_b32_e32 v225, v227
	global_store_dwordx4 v[228:229], v[224:227], off offset:128
	v_add_u32_e32 v66, 0x80, v138
	v_ashrrev_i32_e32 v67, 31, v66
	v_lshlrev_b64 v[64:65], 6, v[66:67]
	v_lshl_add_u64 v[64:65], s[28:29], 0, v[64:65]
	s_nop 0
	s_nop 0
	s_nop 0
	s_nop 0
	v_mov_b32_e32 v64, v203
	v_pk_mul_f32 v[60:61], v[60:61], v[64:65] op_sel_hi:[1,0]
	s_nop 0
	v_mul_f32_e32 v65, 0xbfb8aa3b, v60
	v_exp_f32_e32 v65, v65
	s_nop 0
	v_add_f32_e32 v65, 1.0, v65
	v_rcp_f32_e32 v68, v65
	v_mul_f32_e32 v65, 0xbfb8aa3b, v61
	v_exp_f32_e32 v65, v65
	s_nop 0
	v_add_f32_e32 v65, 1.0, v65
	v_rcp_f32_e32 v69, v65
	v_pk_mul_f32 v[56:57], v[56:57], v[64:65] op_sel_hi:[1,0]
	v_pk_mul_f32 v[58:59], v[58:59], v[64:65] op_sel_hi:[1,0]
	v_pk_mul_f32 v[52:53], v[52:53], v[64:65] op_sel_hi:[1,0]
	v_pk_mul_f32 v[60:61], v[60:61], v[68:69]
	v_pk_mul_f32 v[48:49], v[48:49], v[64:65] op_sel_hi:[1,0]
	v_pk_mul_f32 v[56:57], v[56:57], v[60:61]
	v_pk_mul_f32 v[60:61], v[62:63], v[64:65] op_sel_hi:[1,0]
	v_pk_mul_f32 v[50:51], v[50:51], v[64:65] op_sel_hi:[1,0]
	v_mul_f32_e32 v62, 0xbfb8aa3b, v60
	v_mul_f32_e32 v63, 0xbfb8aa3b, v61
	v_exp_f32_e32 v62, v62
	v_exp_f32_e32 v63, v63
	v_add_f32_e32 v62, 1.0, v62
	v_add_f32_e32 v63, 1.0, v63
	v_rcp_f32_e32 v62, v62
	v_rcp_f32_e32 v63, v63
	s_nop 0
	v_pk_mul_f32 v[60:61], v[60:61], v[62:63]
	s_nop 0
	v_pk_mul_f32 v[58:59], v[58:59], v[60:61]
	v_cvt_pk_bf16_f32 v60, v56, v57
	v_cvt_pk_bf16_f32 v61, v58, v59
	v_mul_f32_e32 v58, 0xbfb8aa3b, v52
	v_mul_f32_e32 v59, 0xbfb8aa3b, v53
	v_exp_f32_e32 v58, v58
	v_exp_f32_e32 v59, v59
	v_mad_i64_i32 v[56:57], s[26:27], v66, s49, v[120:121]
	v_add_f32_e32 v58, 1.0, v58
	v_add_f32_e32 v59, 1.0, v59
	v_rcp_f32_e32 v58, v58
	v_rcp_f32_e32 v59, v59
	v_lshl_add_u64 v[56:57], v[56:57], 0, v[122:123]
	v_lshl_add_u64 v[228:229], v[56:57], 0, v[230:231]
	v_mov_b64_e32 v[220:221], v[60:61]
	v_pk_mul_f32 v[52:53], v[52:53], v[58:59]
	s_nop 0
	v_pk_mul_f32 v[48:49], v[48:49], v[52:53]
	v_pk_mul_f32 v[52:53], v[54:55], v[64:65] op_sel_hi:[1,0]
	v_cvt_pk_bf16_f32 v48, v48, v49
	v_mul_f32_e32 v54, 0xbfb8aa3b, v52
	v_mul_f32_e32 v55, 0xbfb8aa3b, v53
	v_exp_f32_e32 v54, v54
	v_exp_f32_e32 v55, v55
	v_add_f32_e32 v54, 1.0, v54
	v_add_f32_e32 v55, 1.0, v55
	v_rcp_f32_e32 v54, v54
	v_rcp_f32_e32 v55, v55
	s_nop 0
	v_pk_mul_f32 v[52:53], v[52:53], v[54:55]
	s_nop 0
	v_pk_mul_f32 v[50:51], v[50:51], v[52:53]
	s_nop 0
	v_cvt_pk_bf16_f32 v49, v50, v51
	v_mov_b64_e32 v[224:225], v[48:49]
	v_add_u32_e32 v50, 0x90, v138
	v_ashrrev_i32_e32 v51, 31, v50
	v_lshlrev_b64 v[48:49], 6, v[50:51]
	v_lshl_add_u64 v[48:49], s[28:29], 0, v[48:49]
	s_nop 0
	s_nop 0
	s_nop 0
	s_nop 0
	v_mov_b32_e32 v48, v207
	v_pk_mul_f32 v[44:45], v[44:45], v[48:49] op_sel_hi:[1,0]
	s_nop 0
	v_mul_f32_e32 v49, 0xbfb8aa3b, v44
	v_exp_f32_e32 v49, v49
	s_nop 0
	v_add_f32_e32 v49, 1.0, v49
	v_rcp_f32_e32 v52, v49
	v_mul_f32_e32 v49, 0xbfb8aa3b, v45
	v_exp_f32_e32 v49, v49
	s_nop 0
	v_add_f32_e32 v49, 1.0, v49
	v_rcp_f32_e32 v53, v49
	v_pk_mul_f32 v[40:41], v[40:41], v[48:49] op_sel_hi:[1,0]
	v_pk_mul_f32 v[42:43], v[42:43], v[48:49] op_sel_hi:[1,0]
	v_pk_mul_f32 v[36:37], v[36:37], v[48:49] op_sel_hi:[1,0]
	v_pk_mul_f32 v[44:45], v[44:45], v[52:53]
	v_pk_mul_f32 v[32:33], v[32:33], v[48:49] op_sel_hi:[1,0]
	v_pk_mul_f32 v[40:41], v[40:41], v[44:45]
	v_pk_mul_f32 v[44:45], v[46:47], v[48:49] op_sel_hi:[1,0]
	v_pk_mul_f32 v[34:35], v[34:35], v[48:49] op_sel_hi:[1,0]
	v_mul_f32_e32 v46, 0xbfb8aa3b, v44
	v_mul_f32_e32 v47, 0xbfb8aa3b, v45
	v_exp_f32_e32 v46, v46
	v_exp_f32_e32 v47, v47
	v_add_f32_e32 v46, 1.0, v46
	v_add_f32_e32 v47, 1.0, v47
	v_rcp_f32_e32 v46, v46
	v_rcp_f32_e32 v47, v47
	s_nop 0
	v_pk_mul_f32 v[44:45], v[44:45], v[46:47]
	s_nop 0
	v_pk_mul_f32 v[42:43], v[42:43], v[44:45]
	v_cvt_pk_bf16_f32 v44, v40, v41
	v_cvt_pk_bf16_f32 v45, v42, v43
	v_mul_f32_e32 v42, 0xbfb8aa3b, v36
	v_mul_f32_e32 v43, 0xbfb8aa3b, v37
	v_exp_f32_e32 v42, v42
	v_exp_f32_e32 v43, v43
	v_mad_i64_i32 v[40:41], s[26:27], v50, s49, v[120:121]
	v_add_f32_e32 v42, 1.0, v42
	v_add_f32_e32 v43, 1.0, v43
	v_rcp_f32_e32 v42, v42
	v_rcp_f32_e32 v43, v43
	v_lshl_add_u64 v[40:41], v[40:41], 0, v[122:123]
	v_mov_b64_e32 v[222:223], v[44:45]
	s_nop 1
	v_permlane16_swap_b32_e32 v220, v222
	v_permlane16_swap_b32_e32 v221, v223
	global_store_dwordx4 v[228:229], v[220:223], off
	v_pk_mul_f32 v[36:37], v[36:37], v[42:43]
	s_nop 0
	v_pk_mul_f32 v[32:33], v[32:33], v[36:37]
	v_pk_mul_f32 v[36:37], v[38:39], v[48:49] op_sel_hi:[1,0]
	v_cvt_pk_bf16_f32 v32, v32, v33
	v_mul_f32_e32 v38, 0xbfb8aa3b, v36
	v_mul_f32_e32 v39, 0xbfb8aa3b, v37
	v_exp_f32_e32 v38, v38
	v_exp_f32_e32 v39, v39
	v_add_f32_e32 v38, 1.0, v38
	v_add_f32_e32 v39, 1.0, v39
	v_rcp_f32_e32 v38, v38
	v_rcp_f32_e32 v39, v39
	s_nop 0
	v_pk_mul_f32 v[36:37], v[36:37], v[38:39]
	s_nop 0
	v_pk_mul_f32 v[34:35], v[34:35], v[36:37]
	s_nop 0
	v_cvt_pk_bf16_f32 v33, v34, v35
	v_mov_b64_e32 v[226:227], v[32:33]
	s_nop 1
	v_permlane16_swap_b32_e32 v224, v226
	v_permlane16_swap_b32_e32 v225, v227
	global_store_dwordx4 v[228:229], v[224:227], off offset:128
	v_add_u32_e32 v34, 0xa0, v138
	v_ashrrev_i32_e32 v35, 31, v34
	v_lshlrev_b64 v[32:33], 6, v[34:35]
	v_lshl_add_u64 v[32:33], s[28:29], 0, v[32:33]
	s_nop 0
	s_nop 0
	s_nop 0
	s_nop 0
	v_mov_b32_e32 v32, v211
	v_pk_mul_f32 v[28:29], v[28:29], v[32:33] op_sel_hi:[1,0]
	s_nop 0
	v_mul_f32_e32 v33, 0xbfb8aa3b, v28
	v_exp_f32_e32 v33, v33
	s_nop 0
	v_add_f32_e32 v33, 1.0, v33
	v_rcp_f32_e32 v36, v33
	v_mul_f32_e32 v33, 0xbfb8aa3b, v29
	v_exp_f32_e32 v33, v33
	s_nop 0
	v_add_f32_e32 v33, 1.0, v33
	v_rcp_f32_e32 v37, v33
	v_pk_mul_f32 v[24:25], v[24:25], v[32:33] op_sel_hi:[1,0]
	v_pk_mul_f32 v[26:27], v[26:27], v[32:33] op_sel_hi:[1,0]
	v_pk_mul_f32 v[20:21], v[20:21], v[32:33] op_sel_hi:[1,0]
	v_pk_mul_f32 v[28:29], v[28:29], v[36:37]
	v_pk_mul_f32 v[16:17], v[16:17], v[32:33] op_sel_hi:[1,0]
	v_pk_mul_f32 v[24:25], v[24:25], v[28:29]
	v_pk_mul_f32 v[28:29], v[30:31], v[32:33] op_sel_hi:[1,0]
	v_pk_mul_f32 v[18:19], v[18:19], v[32:33] op_sel_hi:[1,0]
	v_mul_f32_e32 v30, 0xbfb8aa3b, v28
	v_mul_f32_e32 v31, 0xbfb8aa3b, v29
	v_exp_f32_e32 v30, v30
	v_exp_f32_e32 v31, v31
	v_add_f32_e32 v30, 1.0, v30
	v_add_f32_e32 v31, 1.0, v31
	v_rcp_f32_e32 v30, v30
	v_rcp_f32_e32 v31, v31
	s_nop 0
	v_pk_mul_f32 v[28:29], v[28:29], v[30:31]
	s_nop 0
	v_pk_mul_f32 v[26:27], v[26:27], v[28:29]
	v_cvt_pk_bf16_f32 v28, v24, v25
	v_cvt_pk_bf16_f32 v29, v26, v27
	v_mul_f32_e32 v26, 0xbfb8aa3b, v20
	v_mul_f32_e32 v27, 0xbfb8aa3b, v21
	v_exp_f32_e32 v26, v26
	v_exp_f32_e32 v27, v27
	v_mad_i64_i32 v[24:25], s[26:27], v34, s49, v[120:121]
	v_add_f32_e32 v26, 1.0, v26
	v_add_f32_e32 v27, 1.0, v27
	v_rcp_f32_e32 v26, v26
	v_rcp_f32_e32 v27, v27
	v_lshl_add_u64 v[24:25], v[24:25], 0, v[122:123]
	v_lshl_add_u64 v[228:229], v[24:25], 0, v[230:231]
	v_mov_b64_e32 v[220:221], v[28:29]
	v_pk_mul_f32 v[20:21], v[20:21], v[26:27]
	s_nop 0
	v_pk_mul_f32 v[16:17], v[16:17], v[20:21]
	v_pk_mul_f32 v[20:21], v[22:23], v[32:33] op_sel_hi:[1,0]
	v_cvt_pk_bf16_f32 v16, v16, v17
	v_mul_f32_e32 v22, 0xbfb8aa3b, v20
	v_mul_f32_e32 v23, 0xbfb8aa3b, v21
	v_exp_f32_e32 v22, v22
	v_exp_f32_e32 v23, v23
	v_add_f32_e32 v22, 1.0, v22
	v_add_f32_e32 v23, 1.0, v23
	v_rcp_f32_e32 v22, v22
	v_rcp_f32_e32 v23, v23
	s_nop 0
	v_pk_mul_f32 v[20:21], v[20:21], v[22:23]
	s_nop 0
	v_pk_mul_f32 v[18:19], v[18:19], v[20:21]
	s_nop 0
	v_cvt_pk_bf16_f32 v17, v18, v19
	v_mov_b64_e32 v[224:225], v[16:17]
	v_add_u32_e32 v32, 0xb0, v138
	v_ashrrev_i32_e32 v33, 31, v32
	v_lshlrev_b64 v[16:17], 6, v[32:33]
	v_lshl_add_u64 v[28:29], s[28:29], 0, v[16:17]
	s_nop 0
	s_nop 0
	s_nop 0
	s_nop 0
	s_nop 0
	v_mov_b32_e32 v16, v215
	v_pk_mul_f32 v[12:13], v[12:13], v[16:17] op_sel_hi:[1,0]
	s_and_b64 vcc, exec, s[2:3]
	v_mul_f32_e32 v17, 0xbfb8aa3b, v12
	v_exp_f32_e32 v17, v17
	s_nop 0
	v_add_f32_e32 v17, 1.0, v17
	v_rcp_f32_e32 v18, v17
	v_mul_f32_e32 v17, 0xbfb8aa3b, v13
	v_exp_f32_e32 v17, v17
	s_nop 0
	v_add_f32_e32 v17, 1.0, v17
	v_rcp_f32_e32 v19, v17
	v_pk_mul_f32 v[8:9], v[8:9], v[16:17] op_sel_hi:[1,0]
	v_pk_mul_f32 v[10:11], v[10:11], v[16:17] op_sel_hi:[1,0]
	v_pk_mul_f32 v[4:5], v[4:5], v[16:17] op_sel_hi:[1,0]
	v_pk_mul_f32 v[12:13], v[12:13], v[18:19]
	v_pk_mul_f32 v[0:1], v[0:1], v[16:17] op_sel_hi:[1,0]
	v_pk_mul_f32 v[8:9], v[8:9], v[12:13]
	v_pk_mul_f32 v[12:13], v[14:15], v[16:17] op_sel_hi:[1,0]
	v_cvt_pk_bf16_f32 v8, v8, v9
	v_mul_f32_e32 v14, 0xbfb8aa3b, v12
	v_mul_f32_e32 v15, 0xbfb8aa3b, v13
	v_exp_f32_e32 v14, v14
	v_exp_f32_e32 v15, v15
	v_pk_mul_f32 v[2:3], v[2:3], v[16:17] op_sel_hi:[1,0]
	v_add_f32_e32 v14, 1.0, v14
	v_add_f32_e32 v15, 1.0, v15
	v_rcp_f32_e32 v14, v14
	v_rcp_f32_e32 v15, v15
	s_nop 0
	v_pk_mul_f32 v[12:13], v[12:13], v[14:15]
	s_nop 0
	v_pk_mul_f32 v[10:11], v[10:11], v[12:13]
	s_nop 0
	v_cvt_pk_bf16_f32 v9, v10, v11
	v_mad_i64_i32 v[10:11], s[26:27], v32, s49, v[120:121]
	v_lshl_add_u64 v[10:11], v[10:11], 0, v[122:123]
	v_mov_b64_e32 v[222:223], v[8:9]
	s_nop 1
	v_permlane16_swap_b32_e32 v220, v222
	v_permlane16_swap_b32_e32 v221, v223
	global_store_dwordx4 v[228:229], v[220:223], off
	v_mul_f32_e32 v8, 0xbfb8aa3b, v4
	v_mul_f32_e32 v9, 0xbfb8aa3b, v5
	v_exp_f32_e32 v8, v8
	v_exp_f32_e32 v9, v9
	s_mov_b64 s[26:27], -1
	v_add_f32_e32 v8, 1.0, v8
	v_add_f32_e32 v9, 1.0, v9
	v_rcp_f32_e32 v8, v8
	v_rcp_f32_e32 v9, v9
	s_nop 0
	v_pk_mul_f32 v[4:5], v[4:5], v[8:9]
	s_nop 0
	v_pk_mul_f32 v[0:1], v[0:1], v[4:5]
	v_pk_mul_f32 v[4:5], v[6:7], v[16:17] op_sel_hi:[1,0]
	v_cvt_pk_bf16_f32 v0, v0, v1
	v_mul_f32_e32 v6, 0xbfb8aa3b, v4
	v_mul_f32_e32 v7, 0xbfb8aa3b, v5
	v_exp_f32_e32 v6, v6
	v_exp_f32_e32 v7, v7
	v_add_f32_e32 v6, 1.0, v6
	v_add_f32_e32 v7, 1.0, v7
	v_rcp_f32_e32 v6, v6
	v_rcp_f32_e32 v7, v7
	s_nop 0
	v_pk_mul_f32 v[4:5], v[4:5], v[6:7]
	s_nop 0
	v_pk_mul_f32 v[2:3], v[2:3], v[4:5]
	s_nop 0
	v_cvt_pk_bf16_f32 v1, v2, v3
	v_mov_b64_e32 v[226:227], v[0:1]
	s_nop 1
	v_permlane16_swap_b32_e32 v224, v226
	v_permlane16_swap_b32_e32 v225, v227
	global_store_dwordx4 v[228:229], v[224:227], off offset:128
	s_cbranch_vccnz .LBB0_2464
	s_andn2_b64 vcc, exec, s[14:15]
	s_cbranch_vccnz .LBB0_2463
	s_barrier
	s_branch .LBB0_2463
